# t6 + P5 PV waves: last two accumulator groups (8 MFMAs) issued behind the step barrier instead of 3, fills the post-barrier matrix-pipe bubble
# speedup vs baseline: 1.0063x; 1.0016x over previous
; #define SBAR() __builtin_amdgcn_sched_barrier(0)
; #define RS_BAR() do { asm volatile("s_waitcnt lgkmcnt(0)" ::: "memory"); __builtin_amdgcn_s_barrier(); asm volatile("" ::: "memory"); } while (0)
; #define VM0() asm volatile("s_waitcnt vmcnt(0)" ::: "memory")
; #define VM0() asm volatile("s_waitcnt vmcnt(0)" ::: "memory")
; #define VMMA(OD, F) do { OD = __builtin_amdgcn_mfma_f32_32x32x16_bf16(pa0, PKF(F[0], F[1]), OD, 0, 0, 0); OD = __builtin_amdgcn_mfma_f32_32x32x16_bf16(pa1, PKF(F[2], F[3]), OD, 0, 0, 0); \
;       OD = __builtin_amdgcn_mfma_f32_32x32x16_bf16(pa2, PKF(F[4], F[5]), OD, 0, 0, 0); OD = __builtin_amdgcn_mfma_f32_32x32x16_bf16(pa3, PKF(F[6], F[7]), OD, 0, 0, 0); } while (0)
; #define LW(n) do { asm volatile("s_waitcnt lgkmcnt(" #n ")" ::: "memory"); SBAR(); } while (0)
; template <class Epi>
; __device__ __forceinline__ void attn_rs_body(const bf16* __restrict__ Qb, const bf16* __restrict__ Kc, const bf16* __restrict__ V0c, const bf16* __restrict__ V1c, int NT, char* lds, const Epi& epi) {
;     ...
;       const int vb = vb0 + b * 32768;
;       s16x4 fa[8], fb[8];
;       { const int tv = j < NT ? j : NT - 1; VDMA(tv, b ^ 1); }
;       asm volatile("s_waitcnt lgkmcnt(0)" ::: "memory"); SBAR();
;       VRD(fa, 0, 0); VRD(fb, 1, 0); LW(8); VMMA(o[0], fa);
;       VRD(fa, 2, 0); LW(8); VMMA(o[1], fb);
;       VRD(fb, 3, 0); LW(8); VMMA(o[2], fa);
;       VRD(fa, 0, 1); LW(8); VMMA(o[3], fb);
;       VRD(fb, 1, 1); LW(8); VMMA(o[4], fa);
;       VRD(fa, 2, 1); LW(8); VMMA(o[5], fb);
;       VRD(fb, 3, 1); LW(8); VMMA(o[6], fa);
;       LW(0); VMMA(o[7], fb);
;       VM0(); RS_BAR();
;     }
.LBB0_500:
	s_lshl_b32 s72, s72, 15
	v_lshl_add_u64 v[244:245], v[176:177], 0, s[48:49]
	s_add_i32 s72, s51, s72
	v_lshl_add_u64 v[246:247], v[174:175], 0, s[48:49]
	v_lshl_add_u32 v0, s71, 15, v182
	s_waitcnt lgkmcnt(0)
	ds_read_b64_tr_b16 v[146:147], v0 offset:0
	ds_read_b64_tr_b16 v[148:149], v0 offset:0x800
	ds_read_b64_tr_b16 v[150:151], v0 offset:0x1000
	ds_read_b64_tr_b16 v[152:153], v0 offset:0x1800
	ds_read_b64_tr_b16 v[154:155], v0 offset:0x2000
	ds_read_b64_tr_b16 v[156:157], v0 offset:0x2800
	ds_read_b64_tr_b16 v[158:159], v0 offset:0x3000
	ds_read_b64_tr_b16 v[160:161], v0 offset:0x3800
	ds_read_b64_tr_b16 v[184:185], v0 offset:0x200
	ds_read_b64_tr_b16 v[186:187], v0 offset:0xa00
	ds_read_b64_tr_b16 v[188:189], v0 offset:0x1200
	ds_read_b64_tr_b16 v[190:191], v0 offset:0x1a00
	ds_read_b64_tr_b16 v[192:193], v0 offset:0x2200
	ds_read_b64_tr_b16 v[194:195], v0 offset:0x2a00
	ds_read_b64_tr_b16 v[196:197], v0 offset:0x3200
	ds_read_b64_tr_b16 v[198:199], v0 offset:0x3a00
	s_add_i32 m0, s72, 0x8000
	v_lshl_add_u64 v[248:249], v[244:245], 0, s[12:13]
	global_load_lds_dwordx4 v[248:249], off
	s_add_i32 m0, s72, 0xc000
	v_lshl_add_u64 v[250:251], v[244:245], 0, s[14:15]
	global_load_lds_dwordx4 v[250:251], off
	s_waitcnt lgkmcnt(8)
	s_nop 0
	v_mfma_f32_32x32x16_bf16 v[114:129], v[142:145], v[146:149], v[114:129]
	ds_read_b64_tr_b16 v[146:147], v0 offset:0x400
	ds_read_b64_tr_b16 v[148:149], v0 offset:0xc00
	v_mfma_f32_32x32x16_bf16 v[114:129], v[138:141], v[150:153], v[114:129]
	ds_read_b64_tr_b16 v[150:151], v0 offset:0x1400
	ds_read_b64_tr_b16 v[152:153], v0 offset:0x1c00
	s_add_i32 m0, s72, 0x8400
	v_lshl_add_u64 v[248:249], v[244:245], 0, s[16:17]
	global_load_lds_dwordx4 v[248:249], off
	v_mfma_f32_32x32x16_bf16 v[114:129], v[134:137], v[154:157], v[114:129]
	ds_read_b64_tr_b16 v[154:155], v0 offset:0x2400
	ds_read_b64_tr_b16 v[156:157], v0 offset:0x2c00
	v_mfma_f32_32x32x16_bf16 v[114:129], v[130:133], v[158:161], v[114:129]
	ds_read_b64_tr_b16 v[158:159], v0 offset:0x3400
	ds_read_b64_tr_b16 v[160:161], v0 offset:0x3c00
	s_waitcnt lgkmcnt(8)
	s_add_i32 m0, s72, 0xc400
	v_lshl_add_u64 v[250:251], v[244:245], 0, s[18:19]
	global_load_lds_dwordx4 v[250:251], off
	v_mfma_f32_32x32x16_bf16 v[98:113], v[142:145], v[184:187], v[98:113]
	ds_read_b64_tr_b16 v[184:185], v0 offset:0x600
	ds_read_b64_tr_b16 v[186:187], v0 offset:0xe00
	v_mfma_f32_32x32x16_bf16 v[98:113], v[138:141], v[188:191], v[98:113]
	ds_read_b64_tr_b16 v[188:189], v0 offset:0x1600
	ds_read_b64_tr_b16 v[190:191], v0 offset:0x1e00
	s_add_i32 m0, s72, 0x8800
	v_lshl_add_u64 v[248:249], v[246:247], 0, s[12:13]
	global_load_lds_dwordx4 v[248:249], off
	v_mfma_f32_32x32x16_bf16 v[98:113], v[134:137], v[192:195], v[98:113]
	ds_read_b64_tr_b16 v[192:193], v0 offset:0x2600
	ds_read_b64_tr_b16 v[194:195], v0 offset:0x2e00
	v_mfma_f32_32x32x16_bf16 v[98:113], v[130:133], v[196:199], v[98:113]
	ds_read_b64_tr_b16 v[196:197], v0 offset:0x3600
	ds_read_b64_tr_b16 v[198:199], v0 offset:0x3e00
	s_waitcnt lgkmcnt(8)
	s_add_i32 m0, s72, 0xc800
	v_lshl_add_u64 v[250:251], v[246:247], 0, s[14:15]
	global_load_lds_dwordx4 v[250:251], off
	v_mfma_f32_32x32x16_bf16 v[82:97], v[142:145], v[146:149], v[82:97]
	ds_read_b64_tr_b16 v[146:147], v0 offset:0x4000
	ds_read_b64_tr_b16 v[148:149], v0 offset:0x4800
	v_mfma_f32_32x32x16_bf16 v[82:97], v[138:141], v[150:153], v[82:97]
	ds_read_b64_tr_b16 v[150:151], v0 offset:0x5000
	ds_read_b64_tr_b16 v[152:153], v0 offset:0x5800
	s_add_i32 m0, s72, 0x8c00
	v_lshl_add_u64 v[248:249], v[246:247], 0, s[16:17]
	global_load_lds_dwordx4 v[248:249], off
	v_mfma_f32_32x32x16_bf16 v[82:97], v[134:137], v[154:157], v[82:97]
	ds_read_b64_tr_b16 v[154:155], v0 offset:0x6000
	ds_read_b64_tr_b16 v[156:157], v0 offset:0x6800
	v_mfma_f32_32x32x16_bf16 v[82:97], v[130:133], v[158:161], v[82:97]
	ds_read_b64_tr_b16 v[158:159], v0 offset:0x7000
	ds_read_b64_tr_b16 v[160:161], v0 offset:0x7800
	s_waitcnt lgkmcnt(8)
	s_add_i32 m0, s72, 0xcc00
	v_lshl_add_u64 v[250:251], v[246:247], 0, s[18:19]
	global_load_lds_dwordx4 v[250:251], off
	v_mfma_f32_32x32x16_bf16 v[66:81], v[142:145], v[184:187], v[66:81]
	ds_read_b64_tr_b16 v[184:185], v0 offset:0x4200
	ds_read_b64_tr_b16 v[186:187], v0 offset:0x4a00
	v_mfma_f32_32x32x16_bf16 v[66:81], v[138:141], v[188:191], v[66:81]
	ds_read_b64_tr_b16 v[188:189], v0 offset:0x5200
	ds_read_b64_tr_b16 v[190:191], v0 offset:0x5a00
	v_mfma_f32_32x32x16_bf16 v[66:81], v[134:137], v[192:195], v[66:81]
	ds_read_b64_tr_b16 v[192:193], v0 offset:0x6200
	ds_read_b64_tr_b16 v[194:195], v0 offset:0x6a00
	v_mfma_f32_32x32x16_bf16 v[66:81], v[130:133], v[196:199], v[66:81]
	ds_read_b64_tr_b16 v[196:197], v0 offset:0x7200
	ds_read_b64_tr_b16 v[198:199], v0 offset:0x7a00
	s_waitcnt lgkmcnt(8)
	v_mfma_f32_32x32x16_bf16 v[50:65], v[142:145], v[146:149], v[50:65]
	ds_read_b64_tr_b16 v[146:147], v0 offset:0x4400
	ds_read_b64_tr_b16 v[148:149], v0 offset:0x4c00
	v_mfma_f32_32x32x16_bf16 v[50:65], v[138:141], v[150:153], v[50:65]
	ds_read_b64_tr_b16 v[150:151], v0 offset:0x5400
	ds_read_b64_tr_b16 v[152:153], v0 offset:0x5c00
	v_mfma_f32_32x32x16_bf16 v[50:65], v[134:137], v[154:157], v[50:65]
	ds_read_b64_tr_b16 v[154:155], v0 offset:0x6400
	ds_read_b64_tr_b16 v[156:157], v0 offset:0x6c00
	v_mfma_f32_32x32x16_bf16 v[50:65], v[130:133], v[158:161], v[50:65]
	ds_read_b64_tr_b16 v[158:159], v0 offset:0x7400
	ds_read_b64_tr_b16 v[160:161], v0 offset:0x7c00
	s_waitcnt lgkmcnt(8)
	v_mfma_f32_32x32x16_bf16 v[34:49], v[142:145], v[184:187], v[34:49]
	ds_read_b64_tr_b16 v[184:185], v0 offset:0x4600
	ds_read_b64_tr_b16 v[186:187], v0 offset:0x4e00
	v_mfma_f32_32x32x16_bf16 v[34:49], v[138:141], v[188:191], v[34:49]
	ds_read_b64_tr_b16 v[188:189], v0 offset:0x5600
	ds_read_b64_tr_b16 v[190:191], v0 offset:0x5e00
	v_mfma_f32_32x32x16_bf16 v[34:49], v[134:137], v[192:195], v[34:49]
	ds_read_b64_tr_b16 v[192:193], v0 offset:0x6600
	ds_read_b64_tr_b16 v[194:195], v0 offset:0x6e00
	v_mfma_f32_32x32x16_bf16 v[34:49], v[130:133], v[196:199], v[34:49]
	ds_read_b64_tr_b16 v[196:197], v0 offset:0x7600
	ds_read_b64_tr_b16 v[198:199], v0 offset:0x7e00
	s_waitcnt lgkmcnt(8)
	s_waitcnt lgkmcnt(0)
	s_waitcnt vmcnt(0)
	s_add_i32 s70, s70, 1
	s_waitcnt lgkmcnt(0)
	s_barrier
	s_add_u32 s48, s48, 0x4000
	s_addc_u32 s49, s49, 0
	v_mfma_f32_32x32x16_bf16 v[18:33], v[142:145], v[146:149], v[18:33]
	v_mfma_f32_32x32x16_bf16 v[2:17], v[142:145], v[184:187], v[2:17]
	v_mfma_f32_32x32x16_bf16 v[18:33], v[138:141], v[150:153], v[18:33]
	v_mfma_f32_32x32x16_bf16 v[2:17], v[138:141], v[188:191], v[2:17]
	v_mfma_f32_32x32x16_bf16 v[18:33], v[134:137], v[154:157], v[18:33]
	v_mfma_f32_32x32x16_bf16 v[2:17], v[134:137], v[192:195], v[2:17]
	s_cmp_eq_u32 s48, 0x1fc000
	v_mfma_f32_32x32x16_bf16 v[18:33], v[130:133], v[158:161], v[18:33]
	v_mfma_f32_32x32x16_bf16 v[2:17], v[130:133], v[196:199], v[2:17]
	s_cbranch_scc1 .LBB0_503
